# attention O epilogue: v_permlane32_swap pairs, 8 dwordx4 stores instead of 16 dwordx2 per wave
# speedup vs baseline: 1.0200x; 1.0032x over previous
; __device__ __forceinline__ unsigned cvtpk(float lo, float hi) { return pg8::cvt_pk_bf16(lo, hi); }
; __device__ __forceinline__ void attn_phase(const Params& p, LAS unsigned char* lds) {
;     ...
;             const float ltot = lrun + __shfl_xor(lrun, 32), inv = 1.0f / ltot;
;             bf16* orow = AO + rowq * 1024 + h * 128;
; #pragma unroll
;             for (int d = 0; d < 4; ++d)
; #pragma unroll
;                 for (int g = 0; g < 4; ++g)
;                     *(u32x2*)(orow + d * 32 + 8 * g + 4 * hi) = (u32x2){cvtpk(o[d][4 * g] * inv, o[d][4 * g + 1] * inv), cvtpk(o[d][4 * g + 2] * inv, o[d][4 * g + 3] * inv)};
.LBB0_636:
	ds_bpermute_b32 v64, v241, v84
	s_waitcnt lgkmcnt(0)
	s_barrier
	v_add_f32_e32 v64, v84, v64
	v_div_scale_f32 v65, s[44:45], v64, v64, 1.0
	v_rcp_f32_e32 v66, v65
	v_div_scale_f32 v67, vcc, 1.0, v64, 1.0
	s_mov_b64 s[44:45], 0
	v_fma_f32 v68, -v65, v66, 1.0
	v_fmac_f32_e32 v66, v68, v66
	v_mul_f32_e32 v68, v67, v66
	v_fma_f32 v69, -v65, v68, v67
	v_fmac_f32_e32 v68, v69, v66
	v_fma_f32 v65, -v65, v68, v67
	v_div_fmas_f32 v65, v65, v66, v68
	v_div_fixup_f32 v64, v65, v64, 1.0
	v_lshl_add_u64 v[66:67], v[210:211], 0, v[226:227]
	v_mbcnt_lo_u32_b32 v68, -1, 0
	v_mbcnt_hi_u32_b32 v68, -1, v68
	v_and_b32_e32 v68, 32, v68
	v_lshrrev_b32_e32 v68, 2, v68
	v_mov_b32_e32 v69, 0
	v_lshl_add_u64 v[66:67], v[66:67], 0, v[68:69]
	v_pk_mul_f32 v[48:49], v[48:49], v[64:65] op_sel_hi:[1,0]
	v_pk_mul_f32 v[50:51], v[50:51], v[64:65] op_sel_hi:[1,0]
	v_pk_mul_f32 v[52:53], v[52:53], v[64:65] op_sel_hi:[1,0]
	v_pk_mul_f32 v[54:55], v[54:55], v[64:65] op_sel_hi:[1,0]
	v_cvt_pk_bf16_f32 v48, v48, v49
	v_cvt_pk_bf16_f32 v49, v50, v51
	v_cvt_pk_bf16_f32 v50, v52, v53
	v_cvt_pk_bf16_f32 v51, v54, v55
	s_nop 1
	v_permlane32_swap_b32_e32 v48, v50
	v_permlane32_swap_b32_e32 v49, v51
	global_store_dwordx4 v[66:67], v[48:51], off
	v_pk_mul_f32 v[56:57], v[56:57], v[64:65] op_sel_hi:[1,0]
	v_pk_mul_f32 v[58:59], v[58:59], v[64:65] op_sel_hi:[1,0]
	v_pk_mul_f32 v[60:61], v[60:61], v[64:65] op_sel_hi:[1,0]
	v_pk_mul_f32 v[62:63], v[62:63], v[64:65] op_sel_hi:[1,0]
	v_cvt_pk_bf16_f32 v56, v56, v57
	v_cvt_pk_bf16_f32 v57, v58, v59
	v_cvt_pk_bf16_f32 v58, v60, v61
	v_cvt_pk_bf16_f32 v59, v62, v63
	s_nop 1
	v_permlane32_swap_b32_e32 v56, v58
	v_permlane32_swap_b32_e32 v57, v59
	global_store_dwordx4 v[66:67], v[56:59], off offset:32
	v_pk_mul_f32 v[32:33], v[32:33], v[64:65] op_sel_hi:[1,0]
	v_pk_mul_f32 v[34:35], v[34:35], v[64:65] op_sel_hi:[1,0]
	v_pk_mul_f32 v[36:37], v[36:37], v[64:65] op_sel_hi:[1,0]
	v_pk_mul_f32 v[38:39], v[38:39], v[64:65] op_sel_hi:[1,0]
	v_cvt_pk_bf16_f32 v32, v32, v33
	v_cvt_pk_bf16_f32 v33, v34, v35
	v_cvt_pk_bf16_f32 v34, v36, v37
	v_cvt_pk_bf16_f32 v35, v38, v39
	s_nop 1
	v_permlane32_swap_b32_e32 v32, v34
	v_permlane32_swap_b32_e32 v33, v35
	global_store_dwordx4 v[66:67], v[32:35], off offset:64
	v_pk_mul_f32 v[40:41], v[40:41], v[64:65] op_sel_hi:[1,0]
	v_pk_mul_f32 v[42:43], v[42:43], v[64:65] op_sel_hi:[1,0]
	v_pk_mul_f32 v[44:45], v[44:45], v[64:65] op_sel_hi:[1,0]
	v_pk_mul_f32 v[46:47], v[46:47], v[64:65] op_sel_hi:[1,0]
	v_cvt_pk_bf16_f32 v40, v40, v41
	v_cvt_pk_bf16_f32 v41, v42, v43
	v_cvt_pk_bf16_f32 v42, v44, v45
	v_cvt_pk_bf16_f32 v43, v46, v47
	s_nop 1
	v_permlane32_swap_b32_e32 v40, v42
	v_permlane32_swap_b32_e32 v41, v43
	global_store_dwordx4 v[66:67], v[40:43], off offset:96
	v_pk_mul_f32 v[16:17], v[16:17], v[64:65] op_sel_hi:[1,0]
	v_pk_mul_f32 v[18:19], v[18:19], v[64:65] op_sel_hi:[1,0]
	v_pk_mul_f32 v[20:21], v[20:21], v[64:65] op_sel_hi:[1,0]
	v_pk_mul_f32 v[22:23], v[22:23], v[64:65] op_sel_hi:[1,0]
	v_cvt_pk_bf16_f32 v16, v16, v17
	v_cvt_pk_bf16_f32 v17, v18, v19
	v_cvt_pk_bf16_f32 v18, v20, v21
	v_cvt_pk_bf16_f32 v19, v22, v23
	s_nop 1
	v_permlane32_swap_b32_e32 v16, v18
	v_permlane32_swap_b32_e32 v17, v19
	global_store_dwordx4 v[66:67], v[16:19], off offset:128
	v_pk_mul_f32 v[24:25], v[24:25], v[64:65] op_sel_hi:[1,0]
	v_pk_mul_f32 v[26:27], v[26:27], v[64:65] op_sel_hi:[1,0]
	v_pk_mul_f32 v[28:29], v[28:29], v[64:65] op_sel_hi:[1,0]
	v_pk_mul_f32 v[30:31], v[30:31], v[64:65] op_sel_hi:[1,0]
	v_cvt_pk_bf16_f32 v24, v24, v25
	v_cvt_pk_bf16_f32 v25, v26, v27
	v_cvt_pk_bf16_f32 v26, v28, v29
	v_cvt_pk_bf16_f32 v27, v30, v31
	s_nop 1
	v_permlane32_swap_b32_e32 v24, v26
	v_permlane32_swap_b32_e32 v25, v27
	global_store_dwordx4 v[66:67], v[24:27], off offset:160
	v_pk_mul_f32 v[0:1], v[0:1], v[64:65] op_sel_hi:[1,0]
	v_pk_mul_f32 v[2:3], v[2:3], v[64:65] op_sel_hi:[1,0]
	v_pk_mul_f32 v[4:5], v[4:5], v[64:65] op_sel_hi:[1,0]
	v_pk_mul_f32 v[6:7], v[6:7], v[64:65] op_sel_hi:[1,0]
	v_cvt_pk_bf16_f32 v0, v0, v1
	v_cvt_pk_bf16_f32 v1, v2, v3
	v_cvt_pk_bf16_f32 v2, v4, v5
	v_cvt_pk_bf16_f32 v3, v6, v7
	s_nop 1
	v_permlane32_swap_b32_e32 v0, v2
	v_permlane32_swap_b32_e32 v1, v3
	global_store_dwordx4 v[66:67], v[0:3], off offset:192
	v_pk_mul_f32 v[8:9], v[8:9], v[64:65] op_sel_hi:[1,0]
	v_pk_mul_f32 v[10:11], v[10:11], v[64:65] op_sel_hi:[1,0]
	v_pk_mul_f32 v[12:13], v[12:13], v[64:65] op_sel_hi:[1,0]
	v_pk_mul_f32 v[14:15], v[14:15], v[64:65] op_sel_hi:[1,0]
	v_cvt_pk_bf16_f32 v8, v8, v9
	v_cvt_pk_bf16_f32 v9, v10, v11
	v_cvt_pk_bf16_f32 v10, v12, v13
	v_cvt_pk_bf16_f32 v11, v14, v15
	s_nop 1
	v_permlane32_swap_b32_e32 v8, v10
	v_permlane32_swap_b32_e32 v9, v11
	global_store_dwordx4 v[66:67], v[8:11], off offset:224
	s_and_b64 vcc, exec, s[42:43]
	s_nop 1
	s_cbranch_vccnz .LBB0_634
